# de-serialised prologue ladders: LN1 gate-weight copy (16 loads then one wait) and the attention lambda dot products (one fetch per lane staged in per-wave LDS, same fma order); on top of the P7 counte
# speedup vs baseline: 1.0127x; 1.0083x over previous
; #define SYNC() __syncthreads()
; template <bool WRITE_BF16, bool GATES>
; __device__ __forceinline__ void ln_phase(const Args& a, LAS unsigned char* lds, float* hbuf, const float* g, const float* b) {
;     ...
;     if (GATES) { const float* wg = (const float*)(a.ws + WS_WG); for (int i = tid; i < 8 * D; i += 512) wgs[i] = wg[i]; SYNC(); }
;     f32x4 gv[4], bv[4];
; #pragma unroll
;     for (int j = 0; j < 4; ++j) { gv[j] = *(const f32x4*)(g + 4 * lane + 256 * j); bv[j] = *(const f32x4*)(b + 4 * lane + 256 * j); }
;     bf16_t* xb = (bf16_t*)(a.ws + WS_XB); float* gate = (float*)(a.ws + WS_GATE);
;     const int gw = blockIdx.x * 8 + wid, NGW = gridDim.x * 8;
;     for (int m0 = 2 * gw; m0 < M; m0 += 2 * NGW) {
;         f32x4 vv[2][4];
; #pragma unroll
;         for (int rr = 0; rr < 2; ++rr) { const f32x4* xr = (const f32x4*)(hbuf + (size_t)(m0 + rr) * D) + lane;
; #pragma unroll
;             for (int j = 0; j < 4; ++j) vv[rr][j] = xr[64 * j]; }
.LBB0_228:
	s_nop 0
	v_readlane_b32 s2, v238, 21
	v_readlane_b32 s3, v238, 22
	s_cmp_lt_i32 s2, 4
	s_cselect_b64 s[0:1], -1, 0
	s_cmp_gt_i32 s3, 3
	s_cselect_b64 s[2:3], -1, 0
	s_and_b64 s[0:1], s[0:1], s[2:3]
	s_andn2_b64 vcc, exec, s[0:1]
	s_cbranch_vccnz .LBB0_304
	v_and_b32_e32 v194, 0x3ff, v0
	s_add_u32 s0, s86, 0x2c00000
	v_mov_b32_e32 v5, 0
	s_addc_u32 s1, s87, 0
	v_lshlrev_b32_e32 v2, 2, v194
	v_add_u32_e32 v3, 0x1000, v2
	v_add_u32_e32 v4, 0x2000, v2
	v_add_u32_e32 v5, 0x3000, v2
	v_add_u32_e32 v6, 0x4000, v2
	v_add_u32_e32 v7, 0x5000, v2
	v_add_u32_e32 v8, 0x6000, v2
	v_add_u32_e32 v9, 0x7000, v2
	global_load_dword v10, v2, s[0:1]
	global_load_dword v11, v2, s[0:1] offset:2048
	global_load_dword v12, v3, s[0:1]
	global_load_dword v13, v3, s[0:1] offset:2048
	global_load_dword v14, v4, s[0:1]
	global_load_dword v15, v4, s[0:1] offset:2048
	global_load_dword v16, v5, s[0:1]
	global_load_dword v17, v5, s[0:1] offset:2048
	global_load_dword v18, v6, s[0:1]
	global_load_dword v19, v6, s[0:1] offset:2048
	global_load_dword v20, v7, s[0:1]
	global_load_dword v21, v7, s[0:1] offset:2048
	global_load_dword v22, v8, s[0:1]
	global_load_dword v23, v8, s[0:1] offset:2048
	global_load_dword v24, v9, s[0:1]
	global_load_dword v25, v9, s[0:1] offset:2048
	s_waitcnt vmcnt(0)
	ds_write2st64_b32 v2, v10, v11 offset1:8
	ds_write2st64_b32 v2, v12, v13 offset0:16 offset1:24
	ds_write2st64_b32 v2, v14, v15 offset0:32 offset1:40
	ds_write2st64_b32 v2, v16, v17 offset0:48 offset1:56
	ds_write2st64_b32 v2, v18, v19 offset0:64 offset1:72
	ds_write2st64_b32 v2, v20, v21 offset0:80 offset1:88
	ds_write2st64_b32 v2, v22, v23 offset0:96 offset1:104
	ds_write2st64_b32 v2, v24, v25 offset0:112 offset1:120
	v_readlane_b32 s0, v238, 23
	v_lshrrev_b32_e32 v1, 5, v194
	v_readlane_b32 s1, v238, 24
	v_and_b32_e32 v1, 30, v1
	s_xor_b64 s[2:3], s[0:1], -1
	v_lshl_add_u32 v196, s92, 4, v1
	s_mov_b32 s0, 0x8000
	v_cmp_gt_i32_e32 vcc, s0, v196
	s_waitcnt lgkmcnt(0)
	s_barrier
	s_and_saveexec_b64 s[20:21], vcc
	s_cbranch_execz .LBB0_247
	v_and_b32_e32 v1, 63, v194
	v_lshlrev_b32_e32 v168, 4, v1
	global_load_dwordx4 v[2:5], v168, s[14:15]
	global_load_dwordx4 v[6:9], v168, s[16:17]
	global_load_dwordx4 v[10:13], v168, s[14:15] offset:1024
	global_load_dwordx4 v[14:17], v168, s[16:17] offset:1024
	global_load_dwordx4 v[18:21], v168, s[14:15] offset:2048
	global_load_dwordx4 v[22:25], v168, s[16:17] offset:2048
	global_load_dwordx4 v[26:29], v168, s[14:15] offset:3072
	global_load_dwordx4 v[30:33], v168, s[16:17] offset:3072
	v_add_u32_e32 v158, 0, v168
	ds_read_b128 v[34:37], v158
	ds_read_b128 v[38:41], v158 offset:1024
	ds_read_b128 v[42:45], v158 offset:2048
	ds_read_b128 v[46:49], v158 offset:3072
	ds_read_b128 v[50:53], v158 offset:4096
	ds_read_b128 v[54:57], v158 offset:5120
	ds_read_b128 v[58:61], v158 offset:6144
	ds_read_b128 v[62:65], v158 offset:7168
	ds_read_b128 v[66:69], v158 offset:8192
	ds_read_b128 v[70:73], v158 offset:9216
	ds_read_b128 v[74:77], v158 offset:10240
	ds_read_b128 v[78:81], v158 offset:11264
	ds_read_b128 v[82:85], v158 offset:12288
	ds_read_b128 v[86:89], v158 offset:13312
	ds_read_b128 v[90:93], v158 offset:14336
	ds_read_b128 v[94:97], v158 offset:15360
	ds_read_b128 v[98:101], v158 offset:16384
	ds_read_b128 v[102:105], v158 offset:17408
	ds_read_b128 v[106:109], v158 offset:18432
	ds_read_b128 v[110:113], v158 offset:19456
	ds_read_b128 v[114:117], v158 offset:20480
	ds_read_b128 v[118:121], v158 offset:21504
	ds_read_b128 v[122:125], v158 offset:22528
	ds_read_b128 v[126:129], v158 offset:23552
	ds_read_b128 v[130:133], v158 offset:24576
	ds_read_b128 v[134:137], v158 offset:25600
	ds_read_b128 v[138:141], v158 offset:26624
	ds_read_b128 v[142:145], v158 offset:27648
	ds_read_b128 v[146:149], v158 offset:28672
	ds_read_b128 v[150:153], v158 offset:29696
	ds_read_b128 v[154:157], v158 offset:30720
	ds_read_b128 v[158:161], v158 offset:31744
	v_lshlrev_b32_e32 v162, 2, v1
	v_mov_b32_e32 v163, 0
	v_lshl_add_u64 v[166:167], s[38:39], 0, v[162:163]
	v_lshl_add_u64 v[164:165], s[36:37], 0, v[162:163]
	v_lshl_add_u64 v[166:167], v[166:167], 0, -16
	v_cmp_gt_u32_e32 vcc, 4, v1
	v_ashrrev_i32_e32 v197, 31, v196
	s_lshl_b32 s22, s88, 4
	v_cndmask_b32_e32 v199, v167, v165, vcc
	v_cndmask_b32_e32 v198, v166, v164, vcc
	v_lshlrev_b64 v[164:165], 5, v[196:197]
	v_lshl_add_u64 v[200:201], v[164:165], 0, v[162:163]
	v_lshlrev_b64 v[162:163], 12, v[196:197]
	v_or_b32_e32 v162, v162, v168
	s_ashr_i32 s23, s22, 31
	v_lshlrev_b64 v[202:203], 11, v[196:197]
	v_lshl_add_u64 v[162:163], s[84:85], 0, v[162:163]
	s_mov_b64 s[18:19], 0x1000
	v_cmp_gt_u32_e64 s[0:1], 8, v1
	v_cmp_eq_u32_e64 s[4:5], 1, v1
	v_cmp_eq_u32_e64 s[6:7], 2, v1
	v_cmp_eq_u32_e64 s[8:9], 3, v1
	v_cmp_eq_u32_e64 s[10:11], 4, v1
	v_cmp_eq_u32_e64 s[12:13], 5, v1
	v_cmp_eq_u32_e64 s[14:15], 6, v1
	v_cmp_eq_u32_e64 s[16:17], 7, v1
	s_lshl_b64 s[28:29], s[22:23], 5
	v_lshl_or_b32 v202, v1, 3, v202
	s_lshl_b64 s[30:31], s[22:23], 11
	v_lshl_add_u64 v[204:205], v[162:163], 0, s[18:19]
	s_lshl_b64 s[34:35], s[22:23], 12
	s_mov_b64 s[36:37], 0
	v_mov_b32_e32 v1, 0x3727c5ac
	s_mov_b32 s23, 0xf800000
	v_mov_b32_e32 v195, 0x260
	s_mov_b32 s33, 0x3000000
	s_movk_i32 s38, 0x7fff
	s_branch .LBB0_243

; __global__ void __launch_bounds__(512) fwd_kernel(Args a) {
;     ...
;         { float s1 = 0.f, s2 = 0.f;
;           for (int i = 0; i < 64; ++i) { s1 += a.in[10][i] * a.in[11][i]; s2 += a.in[12][i] * a.in[13][i]; }
;           lam = expf(s1) - expf(s2) + LAMBDA_INIT; }
.LBB0_482:
	v_readlane_b32 s0, v238, 23
	v_readlane_b32 s1, v238, 24
	v_mov_b32_e32 v4, 0
	s_xor_b64 s[12:13], s[0:1], -1
	s_mov_b64 s[0:1], 0
	v_mov_b32_e32 v2, 0
	v_mov_b32_e32 v3, v4
	v_and_b32_e32 v5, 63, v1
	v_lshlrev_b32_e32 v5, 2, v5
	s_waitcnt lgkmcnt(0)
	global_load_dword v6, v5, s[40:41]
	global_load_dword v7, v5, s[42:43]
	global_load_dword v8, v5, s[44:45]
	global_load_dword v9, v5, s[46:47]
	v_lshrrev_b32_e32 v41, 6, v1
	v_lshlrev_b32_e32 v41, 10, v41
	v_add_u32_e32 v42, v41, v5
	s_waitcnt vmcnt(0)
	ds_write_b32 v42, v6
	ds_write_b32 v42, v7 offset:256
	ds_write_b32 v42, v8 offset:512
	ds_write_b32 v42, v9 offset:768
	s_waitcnt lgkmcnt(0)
.LBB0_483:
	v_add_u32_e32 v40, s0, v41
	ds_read_b128 v[6:9], v40
	ds_read_b128 v[10:13], v40 offset:16
	ds_read_b128 v[14:17], v40 offset:256
	ds_read_b128 v[18:21], v40 offset:272
	ds_read_b128 v[22:25], v40 offset:512
	ds_read_b128 v[26:29], v40 offset:528
	ds_read_b128 v[30:33], v40 offset:768
	ds_read_b128 v[34:37], v40 offset:784
	s_add_u32 s0, s0, 32
	s_addc_u32 s1, s1, 0
	s_cmpk_eq_i32 s0, 0x100
	s_waitcnt lgkmcnt(0)
	v_mov_b32_e32 v38, v6
	v_mov_b32_e32 v6, v8
	v_mov_b32_e32 v8, v10
	v_mov_b32_e32 v10, v12
	v_mov_b32_e32 v12, v14
	v_mov_b32_e32 v14, v16
	v_mov_b32_e32 v39, v22
	v_mov_b32_e32 v22, v7
	v_mov_b32_e32 v7, v24
	v_mov_b32_e32 v24, v9
	v_mov_b32_e32 v9, v26
	v_mov_b32_e32 v26, v11
	v_mov_b32_e32 v11, v28
	v_mov_b32_e32 v28, v13
	v_mov_b32_e32 v13, v30
	v_mov_b32_e32 v30, v15
	v_pk_fma_f32 v[2:3], v[38:39], v[12:13], v[2:3]
	v_mov_b32_e32 v15, v32
	v_pk_fma_f32 v[2:3], v[22:23], v[30:31], v[2:3]
	v_mov_b32_e32 v32, v17
	v_pk_fma_f32 v[2:3], v[6:7], v[14:15], v[2:3]
	v_mov_b32_e32 v16, v18
	v_mov_b32_e32 v17, v34
	v_pk_fma_f32 v[2:3], v[24:25], v[32:33], v[2:3]
	v_mov_b32_e32 v34, v19
	v_pk_fma_f32 v[2:3], v[8:9], v[16:17], v[2:3]
	v_mov_b32_e32 v18, v20
	v_mov_b32_e32 v19, v36
	v_pk_fma_f32 v[2:3], v[26:27], v[34:35], v[2:3]
	v_mov_b32_e32 v36, v21
	v_pk_fma_f32 v[2:3], v[10:11], v[18:19], v[2:3]
	s_nop 0
	v_pk_fma_f32 v[2:3], v[28:29], v[36:37], v[2:3]
	s_cbranch_scc0 .LBB0_483
	v_mul_f32_e32 v4, 0x3fb8aa3b, v2
	s_mov_b32 s0, 0x3fb8aa3b
	v_rndne_f32_e32 v5, v4
	v_sub_f32_e32 v6, v4, v5
	v_fma_f32 v4, v2, s0, -v4
	v_fmac_f32_e32 v4, 0x32a5705f, v2
	v_add_f32_e32 v4, v6, v4
	v_exp_f32_e32 v4, v4
	v_cvt_i32_f32_e32 v5, v5
	s_mov_b32 s1, 0xc2ce8ed0
	v_cmp_ngt_f32_e32 vcc, s1, v2
	s_mov_b32 s2, 0x42b17218
	v_ldexp_f32 v4, v4, v5
	v_mul_f32_e32 v5, 0x3fb8aa3b, v3
	v_rndne_f32_e32 v6, v5
	v_sub_f32_e32 v7, v5, v6
	v_fma_f32 v5, v3, s0, -v5
	v_fmac_f32_e32 v5, 0x32a5705f, v3
	v_add_f32_e32 v5, v7, v5
	v_exp_f32_e32 v5, v5
	v_cvt_i32_f32_e32 v6, v6
	v_cndmask_b32_e32 v4, 0, v4, vcc
	v_mov_b32_e32 v7, 0x7f800000
	v_cmp_nlt_f32_e32 vcc, s2, v2
	v_lshrrev_b32_e32 v8, 4, v1
	v_mov_b32_e32 v161, 0
	v_cndmask_b32_e32 v2, v7, v4, vcc
	v_ldexp_f32 v4, v5, v6
	v_cmp_ngt_f32_e32 vcc, s1, v3
	v_bfe_u32 v5, v1, 5, 1
	s_add_u32 s16, s86, 0x7000000
	v_cndmask_b32_e32 v4, 0, v4, vcc
	v_cmp_nlt_f32_e32 vcc, s2, v3
	s_movk_i32 s2, 0x100
	v_cmp_gt_u32_e64 s[4:5], s2, v1
	v_cndmask_b32_e32 v3, v7, v4, vcc
	v_sub_f32_e32 v2, v2, v3
	s_movk_i32 s2, 0xbf
	v_add_f32_e32 v159, 0x3e4ccccd, v2
	v_sub_co_u32_e32 v2, vcc, s2, v1
	v_subrev_co_u32_e64 v4, s[6:7], s2, v1
	v_and_b32_e32 v3, 63, v1
	s_nop 0
	v_cndmask_b32_e64 v2, v4, v2, s[6:7]
	v_mul_i32_i24_e32 v4, v2, v2
	v_ffbh_u32_e32 v4, v4
	v_sub_u32_e32 v4, 33, v4
	v_min_u32_e32 v4, 15, v4
	v_cmp_gt_u32_e64 s[6:7], 8, v2
	s_mov_b64 s[2:3], 0x1d000000
	v_lshl_add_u32 v220, v3, 2, 0
	v_cndmask_b32_e64 v2, v4, v2, s[6:7]
	v_lshlrev_b32_e32 v2, 2, v2
	v_or_b32_e32 v4, 64, v2
	v_cndmask_b32_e32 v209, v2, v4, vcc
	v_xor_b32_e32 v2, v8, v1
	v_lshlrev_b32_e32 v2, 3, v2
	v_and_b32_e32 v2, 56, v2
	v_lshlrev_b32_e32 v160, 1, v2
	v_lshl_add_u64 v[6:7], s[86:87], 0, v[160:161]
	v_lshl_add_u64 v[162:163], v[6:7], 0, s[2:3]
	v_lshlrev_b32_e32 v6, 3, v1
	v_cmp_gt_u32_e64 s[6:7], 32, v3
	v_bitop3_b32 v3, v8, 7, v1 bitop3:0x48
	v_and_b32_e32 v158, 31, v1
	s_addc_u32 s17, s87, 0
	s_add_i32 s41, 0, 0x20000
	v_and_b32_e32 v212, 0x70, v6
	v_lshlrev_b32_e32 v6, 2, v5
	v_lshlrev_b32_e32 v160, 4, v3
	s_getreg_b32 s40, hwreg(HW_REG_XCC_ID, 0, 4)
	v_lshlrev_b32_e32 v4, 3, v5
	v_lshlrev_b32_e32 v213, 4, v5
	v_lshlrev_b32_e32 v214, 7, v158
	v_add_u32_e32 v215, 0xbf, v6
	s_add_u32 s43, s86, 0x3000000
	v_sub_u32_e32 v221, v6, v158
	v_lshl_add_u64 v[6:7], s[86:87], 0, v[160:161]
	s_mov_b64 s[2:3], 0x71c0480
	v_lshlrev_b32_e32 v168, 1, v2
	s_movk_i32 s28, 0xff80
	v_mbcnt_lo_u32_b32 v2, -1, 0
	s_mov_b32 s15, 0
	v_cmp_eq_u32_e64 s[0:1], 0, v1
	v_lshl_add_u32 v210, v1, 2, s41
	v_lshrrev_b32_e32 v211, 3, v1
	v_add_u32_e32 v216, 0, v214
	v_or_b32_e32 v217, 32, v213
	v_or_b32_e32 v218, 64, v213
	s_movk_i32 s42, 0x60
	v_or_b32_e32 v219, 0x60, v213
	s_addc_u32 s44, s87, 0
	v_lshlrev_b32_e32 v164, 13, v5
	v_mov_b32_e32 v165, v161
	v_lshl_add_u64 v[166:167], v[6:7], 0, s[2:3]
	s_mov_b64 s[18:19], 0x202000
	s_mov_b64 s[20:21], 0x202180
	s_mov_b64 s[22:23], 0x180
	s_mov_b64 s[24:25], 0x150480
	s_mov_b64 s[26:27], 0x150400
	s_add_i32 s45, 0, 0x20c00
	s_movk_i32 s46, 0x7f
	v_lshlrev_b32_e32 v160, 1, v4
	s_mov_b32 s47, 0x8000
	s_mov_b32 s52, 0xc000
	s_mov_b32 s53, 0x41400000
	s_mov_b32 s29, -1
	s_mov_b64 s[30:31], 0x70000
	v_mov_b32_e32 v222, 0x3727c5ac
	s_mov_b32 s54, 0xf800000
	v_mov_b32_e32 v223, 0x260
	s_mov_b32 s55, 0x3f4ccccd
	s_movk_i32 s56, 0x1000
	s_movk_i32 s57, 0x5000
	s_mov_b32 s58, 0x9000
	s_mov_b32 s59, 0xd000
	v_mbcnt_hi_u32_b32 v224, -1, v2
	s_mov_b32 s60, s40
	s_mov_b32 s61, 0
	s_branch .LBB0_486
